# gate/up epilogue: 60 lgkmcnt waits that guarded the removed ds_bpermutes deleted (no LDS ops remain there); hazards re-checked; 8-byte phase of later code kept
# speedup vs baseline: 1.0050x; 1.0050x over previous
;     __device__ __forceinline__ void operator()(const f32x4 (&acc)[2][2][4][2], const Unit& u, int wr, int wc, int fr, int fq) const {
;         const int f0 = u.pn * HALF + wc * 32 + 8 * fq;
;         const int lane = fr + 16 * fq;
;         const int src1 = ((lane & 48) | ((fr + 15) & 15)) << 2, src2 = ((lane & 48) | ((fr + 14) & 15)) << 2;
;         f32x4 w0[2], w1[2], w2[2], bb[2];
; #pragma unroll
;         for (int n = 0; n < 2; ++n) { w0[n] = *(const f32x4*)(cw + f0 + 4 * n); w1[n] = *(const f32x4*)(cw + dff + f0 + 4 * n); w2[n] = *(const f32x4*)(cw + 2 * dff + f0 + 4 * n); bb[n] = *(const f32x4*)(cb + f0 + 4 * n); }
; #pragma unroll
;         for (int ai = 0; ai < 2; ++ai) {
;             const int rowb = u.pm * BM + ai * HALF + wr * 64, blk = rowb >> 6;
; #pragma unroll
;             for (int m = 0; m < 4; ++m) {
;                 u32x4 wa, wg, wu;
; #pragma unroll
;                 for (int n = 0; n < 2; ++n) {
;                     const f32x4 g = acc[ai][0][m][n], uu = acc[ai][1][m][n], gp = acc[ai][0][m > 0 ? m - 1 : 0][n];
;                     f32x4 r;
; #pragma unroll
;                     for (int e = 0; e < 4; ++e) {
;                         const float s1 = (fr == 15) ? gp[e] : g[e], s2 = (fr >= 14) ? gp[e] : g[e];
;                         const float p1 = __int_as_float(__builtin_amdgcn_ds_bpermute(src1, __float_as_int(s1))), p2 = __int_as_float(__builtin_amdgcn_ds_bpermute(src2, __float_as_int(s2)));
;                         const float c = bb[n][e] + w0[n][e] * p2 + w1[n][e] * p1 + w2[n][e] * g[e];
;                         r[e] = c * uu[e] * __builtin_amdgcn_rcpf(1.0f + __builtin_amdgcn_exp2f(c * -1.4426950408889634f));
;                     }
;                     if (n == 0) { wa.x = cvt_pk_bf16(r[0], r[1]); wa.y = cvt_pk_bf16(r[2], r[3]); wg.x = cvt_pk_bf16(g[0], g[1]); wg.y = cvt_pk_bf16(g[2], g[3]); wu.x = cvt_pk_bf16(uu[0], uu[1]); wu.y = cvt_pk_bf16(uu[2], uu[3]); }
;                     else { wa.z = cvt_pk_bf16(r[0], r[1]); wa.w = cvt_pk_bf16(r[2], r[3]); wg.z = cvt_pk_bf16(g[0], g[1]); wg.w = cvt_pk_bf16(g[2], g[3]); wu.z = cvt_pk_bf16(uu[0], uu[1]); wu.w = cvt_pk_bf16(uu[2], uu[3]); }
;                 }
;                 if (m == 0 && fr < 2) {
;                     *(u32x4*)(hg + (size_t)(blk * 4 + 2 + fr) * dff + f0) = wg; *(u32x4*)(hu + (size_t)(blk * 2 + fr) * dff + f0) = wu;
.LBB0_482:
	v_lshl_or_b32 v196, s45, 7, v216
	v_ashrrev_i32_e32 v197, 31, v196
	v_lshlrev_b64 v[66:67], 2, v[196:197]
	v_lshl_add_u64 v[70:71], s[24:25], 0, v[66:67]
	v_lshl_add_u64 v[72:73], s[38:39], 0, v[66:67]
	v_lshl_add_u64 v[90:91], s[42:43], 0, v[66:67]
	v_lshl_add_u64 v[102:103], s[26:27], 0, v[66:67]
	global_load_dwordx4 v[66:69], v[70:71], off offset:16
	global_load_dwordx4 v[86:89], v[70:71], off
	global_load_dwordx4 v[78:81], v[72:73], off offset:16
	global_load_dwordx4 v[94:97], v[72:73], off
	global_load_dwordx4 v[74:77], v[90:91], off offset:16
	s_nop 0
	global_load_dwordx4 v[90:93], v[90:91], off
	s_nop 0
	global_load_dwordx4 v[70:73], v[102:103], off offset:16
	s_nop 0
	global_load_dwordx4 v[102:105], v[102:103], off
	v_mov_b32_dpp v163, v150 row_ror:2 row_mask:0xf bank_mask:0xf
	v_mov_b32_dpp v167, v152 row_ror:2 row_mask:0xf bank_mask:0xf
	v_mov_b32_dpp v162, v150 row_ror:1 row_mask:0xf bank_mask:0xf
	v_mov_b32_dpp v165, v151 row_ror:2 row_mask:0xf bank_mask:0xf
	v_mov_b32_dpp v166, v152 row_ror:1 row_mask:0xf bank_mask:0xf
	v_mov_b32_dpp v169, v153 row_ror:2 row_mask:0xf bank_mask:0xf
	v_mov_b32_dpp v164, v151 row_ror:1 row_mask:0xf bank_mask:0xf
	v_mov_b32_dpp v168, v153 row_ror:1 row_mask:0xf bank_mask:0xf
	v_mov_b32_dpp v220, v149 row_ror:2 row_mask:0xf bank_mask:0xf
	v_mov_b32_dpp v219, v149 row_ror:1 row_mask:0xf bank_mask:0xf
	s_waitcnt vmcnt(0) lgkmcnt(0)
	v_fma_f32 v220, v69, v220, v73
	v_fma_f32 v167, v88, v167, v104
	v_fma_f32 v163, v86, v163, v102
	v_fma_f32 v169, v89, v169, v105
	v_fmac_f32_e32 v167, v96, v166
	v_fma_f32 v165, v87, v165, v103
	v_fmac_f32_e32 v163, v94, v162
	v_fmac_f32_e32 v169, v97, v168
	v_fmac_f32_e32 v167, v152, v92
	v_fmac_f32_e32 v165, v95, v164
	v_fmac_f32_e32 v163, v150, v90
	v_fmac_f32_e32 v169, v153, v93
	v_mul_f32_e32 v166, v160, v167
	v_mul_f32_e32 v167, 0xbfb8aa3b, v167
	v_fmac_f32_e32 v165, v151, v91
	v_mul_f32_e32 v162, v158, v163
	v_mul_f32_e32 v163, 0xbfb8aa3b, v163
	v_mul_f32_e32 v168, v161, v169
	v_mul_f32_e32 v169, 0xbfb8aa3b, v169
	v_exp_f32_e32 v167, v167
	v_mul_f32_e32 v164, v159, v165
	v_mul_f32_e32 v165, 0xbfb8aa3b, v165
	v_exp_f32_e32 v163, v163
	v_exp_f32_e32 v169, v169
	v_exp_f32_e32 v165, v165
	v_add_f32_e32 v167, 1.0, v167
	v_add_f32_e32 v163, 1.0, v163
	v_add_f32_e32 v169, 1.0, v169
	v_rcp_f32_e32 v167, v167
	v_add_f32_e32 v165, 1.0, v165
	v_rcp_f32_e32 v163, v163
	v_rcp_f32_e32 v169, v169
	v_rcp_f32_e32 v165, v165
	v_mul_f32_e32 v167, v166, v167
	v_mul_f32_e32 v162, v162, v163
	v_mul_f32_e32 v168, v168, v169
	v_mul_f32_e32 v164, v164, v165
	v_cvt_pk_bf16_f32 v166, v162, v164
	v_cvt_pk_bf16_f32 v167, v167, v168
	v_cvt_pk_bf16_f32 v162, v150, v151
	v_cvt_pk_bf16_f32 v163, v152, v153
	v_cvt_pk_bf16_f32 v158, v158, v159
	v_cvt_pk_bf16_f32 v159, v160, v161
	v_mov_b32_dpp v161, v146 row_ror:2 row_mask:0xf bank_mask:0xf
	v_mov_b32_dpp v165, v147 row_ror:2 row_mask:0xf bank_mask:0xf
	v_mov_b32_dpp v169, v148 row_ror:2 row_mask:0xf bank_mask:0xf
	v_mov_b32_dpp v160, v146 row_ror:1 row_mask:0xf bank_mask:0xf
	v_mov_b32_dpp v164, v147 row_ror:1 row_mask:0xf bank_mask:0xf
	v_mov_b32_dpp v168, v148 row_ror:1 row_mask:0xf bank_mask:0xf
	v_fma_f32 v165, v67, v165, v71
	v_fma_f32 v169, v68, v169, v72
	v_fma_f32 v161, v66, v161, v70
	v_fmac_f32_e32 v165, v79, v164
	v_fmac_f32_e32 v169, v80, v168
	v_fmac_f32_e32 v161, v78, v160
	v_fmac_f32_e32 v220, v81, v219
	v_fmac_f32_e32 v169, v148, v76
	v_fmac_f32_e32 v165, v147, v75
	v_fmac_f32_e32 v161, v146, v74
	v_fmac_f32_e32 v220, v149, v77
	v_mul_f32_e32 v168, v156, v169
	v_mul_f32_e32 v169, 0xbfb8aa3b, v169
	v_mul_f32_e32 v164, v155, v165
	v_mul_f32_e32 v165, 0xbfb8aa3b, v165
	v_mul_f32_e32 v160, v154, v161
	v_mul_f32_e32 v161, 0xbfb8aa3b, v161
	v_mul_f32_e32 v219, v157, v220
	v_mul_f32_e32 v220, 0xbfb8aa3b, v220
	v_exp_f32_e32 v169, v169
	v_exp_f32_e32 v165, v165
	v_exp_f32_e32 v161, v161
	v_exp_f32_e32 v220, v220
	v_add_f32_e32 v169, 1.0, v169
	v_add_f32_e32 v165, 1.0, v165
	v_add_f32_e32 v161, 1.0, v161
	v_add_f32_e32 v220, 1.0, v220
	v_rcp_f32_e32 v169, v169
	v_rcp_f32_e32 v165, v165
	v_rcp_f32_e32 v161, v161
	v_rcp_f32_e32 v220, v220
	v_mul_f32_e32 v169, v168, v169
	v_mul_f32_e32 v164, v164, v165
	v_mul_f32_e32 v160, v160, v161
	v_mul_f32_e32 v219, v219, v220
	v_cvt_pk_bf16_f32 v168, v160, v164
	v_cvt_pk_bf16_f32 v169, v169, v219
	v_cvt_pk_bf16_f32 v164, v146, v147
	v_cvt_pk_bf16_f32 v165, v148, v149
	v_cvt_pk_bf16_f32 v160, v154, v155
	v_cvt_pk_bf16_f32 v161, v156, v157
	s_and_saveexec_b64 s[16:17], s[10:11]
	s_xor_b64 s[56:57], exec, s[16:17]
	v_mov_b64_e32 v[158:159], v[166:167]
	v_mov_b64_e32 v[160:161], v[168:169]
	s_or_saveexec_b64 s[56:57], s[56:57]
	s_lshl_b32 s45, s76, 8
	s_add_i32 s45, s45, s5
	v_or_b32_e32 v156, s45, v170
	s_ashr_i32 s47, s45, 4
	v_mov_b64_e32 v[154:155], s[22:23]
	v_mov_b32_e32 v157, v156
	s_xor_b64 exec, exec, s[56:57]
	s_cbranch_execz .LBB0_486
	s_ashr_i32 s16, s45, 5
	v_or_b32_e32 v166, s47, v215
	v_mov_b64_e32 v[154:155], s[28:29]
	v_or_b32_e32 v157, s16, v170
	v_mad_i64_i32 v[154:155], s[16:17], v166, s78, v[154:155]
	v_lshl_add_u64 v[154:155], v[196:197], 1, v[154:155]
	global_store_dwordx4 v[154:155], v[162:165], off
	v_mov_b64_e32 v[154:155], s[30:31]
; __device__ __forceinline__ unsigned cvt_pk_bf16(float lo, float hi) { unsigned r; asm volatile("v_cvt_pk_bf16_f32 %0, %1, %2" : "=v"(r) : "v"(lo), "v"(hi)); return r; }
;     __device__ __forceinline__ void operator()(const f32x4 (&acc)[2][2][4][2], const Unit& u, int wr, int wc, int fr, int fq) const {
;     ...
;                 for (int n = 0; n < 2; ++n) {
;                     const f32x4 g = acc[ai][0][m][n], uu = acc[ai][1][m][n], gp = acc[ai][0][m > 0 ? m - 1 : 0][n];
;                     f32x4 r;
; #pragma unroll
;                     for (int e = 0; e < 4; ++e) {
;                         const float s1 = (fr == 15) ? gp[e] : g[e], s2 = (fr >= 14) ? gp[e] : g[e];
;                         const float p1 = __int_as_float(__builtin_amdgcn_ds_bpermute(src1, __float_as_int(s1))), p2 = __int_as_float(__builtin_amdgcn_ds_bpermute(src2, __float_as_int(s2)));
;                         const float c = bb[n][e] + w0[n][e] * p2 + w1[n][e] * p1 + w2[n][e] * g[e];
;                         r[e] = c * uu[e] * __builtin_amdgcn_rcpf(1.0f + __builtin_amdgcn_exp2f(c * -1.4426950408889634f));
;                     }
;                     if (n == 0) { wa.x = cvt_pk_bf16(r[0], r[1]); wa.y = cvt_pk_bf16(r[2], r[3]); wg.x = cvt_pk_bf16(g[0], g[1]); wg.y = cvt_pk_bf16(g[2], g[3]); wu.x = cvt_pk_bf16(uu[0], uu[1]); wu.y = cvt_pk_bf16(uu[2], uu[3]); }
;                     else { wa.z = cvt_pk_bf16(r[0], r[1]); wa.w = cvt_pk_bf16(r[2], r[3]); wg.z = cvt_pk_bf16(g[0], g[1]); wg.w = cvt_pk_bf16(g[2], g[3]); wu.z = cvt_pk_bf16(uu[0], uu[1]); wu.w = cvt_pk_bf16(uu[2], uu[3]); }
;                 }
;                 if (m == 0 && fr < 2) {
;                     *(u32x4*)(hg + (size_t)(blk * 4 + 2 + fr) * dff + f0) = wg; *(u32x4*)(hu + (size_t)(blk * 2 + fr) * dff + f0) = wu;
;                 } else {
;                     *(u32x4*)(act + (size_t)(rowb + m * 16 + fr) * dff + f0) = wa;
.LBB0_486:
	s_or_b64 exec, exec, s[56:57]
	v_mad_i64_i32 v[162:163], s[16:17], v157, s78, v[154:155]
	v_lshlrev_b64 v[154:155], 1, v[196:197]
	v_lshl_add_u64 v[162:163], v[162:163], 0, v[154:155]
	v_cndmask_b32_e64 v157, v138, v150, s[6:7]
	v_cndmask_b32_e64 v150, v138, v150, s[8:9]
	global_store_dwordx4 v[162:163], v[158:161], off
	s_nop 1
	v_mov_b32_dpp v159, v157 row_ror:1 row_mask:0xf bank_mask:0xf
	v_mov_b32_dpp v157, v150 row_ror:2 row_mask:0xf bank_mask:0xf
	v_cndmask_b32_e64 v150, v139, v151, s[6:7]
	v_cndmask_b32_e64 v151, v139, v151, s[8:9]
	s_nop 1
	v_mov_b32_dpp v161, v150 row_ror:1 row_mask:0xf bank_mask:0xf
	v_cndmask_b32_e64 v150, v140, v152, s[6:7]
	v_cndmask_b32_e64 v152, v140, v152, s[8:9]
	v_mov_b32_dpp v158, v151 row_ror:2 row_mask:0xf bank_mask:0xf
	v_mov_b32_dpp v151, v150 row_ror:1 row_mask:0xf bank_mask:0xf
	v_mov_b32_dpp v160, v152 row_ror:2 row_mask:0xf bank_mask:0xf
	v_cndmask_b32_e64 v150, v141, v153, s[6:7]
	v_cndmask_b32_e64 v152, v141, v153, s[8:9]
	s_nop 1
	v_mov_b32_dpp v153, v150 row_ror:1 row_mask:0xf bank_mask:0xf
	v_mov_b32_dpp v150, v152 row_ror:2 row_mask:0xf bank_mask:0xf
	v_mov_b32_e32 v162, v141
	v_mov_b32_e32 v163, v97
	v_mov_b32_e32 v152, v93
	v_pk_mul_f32 v[152:153], v[162:163], v[152:153]
	v_fma_f32 v150, v89, v150, v105
	v_add_f32_e32 v150, v153, v150
	v_add_f32_e32 v162, v152, v150
	v_mul_f32_e32 v150, 0xbfb8aa3b, v162
	v_exp_f32_e32 v163, v150
	v_mov_b32_e32 v152, v140
	v_mov_b32_e32 v153, v96
	v_mov_b32_e32 v150, v92
	v_pk_mul_f32 v[150:151], v[152:153], v[150:151]
	v_fma_f32 v152, v88, v160, v104
	v_add_f32_e32 v151, v151, v152
	v_add_f32_e32 v151, v150, v151
	v_mul_f32_e32 v150, 0xbfb8aa3b, v151
	v_exp_f32_e32 v152, v150
	v_add_f32_e32 v153, 1.0, v163
	v_rcp_f32_e32 v153, v153
	v_mul_f32_e32 v160, v145, v162
	v_add_f32_e32 v152, 1.0, v152
	v_rcp_f32_e32 v152, v152
	v_mul_f32_e32 v151, v144, v151
	v_mul_f32_e32 v162, v160, v153
	v_mov_b32_e32 v153, v95
	v_mul_f32_e32 v151, v151, v152
	v_mov_b32_e32 v152, v139
	v_mov_b32_e32 v160, v91
	v_pk_mul_f32 v[152:153], v[152:153], v[160:161]
	v_fma_f32 v158, v87, v158, v103
	v_add_f32_e32 v153, v153, v158
	v_add_f32_e32 v160, v152, v153
	v_mul_f32_e32 v152, 0xbfb8aa3b, v160
	v_exp_f32_e32 v161, v152
	v_mov_b32_e32 v152, v138
	v_mov_b32_e32 v153, v94
	v_mov_b32_e32 v158, v90
	v_pk_mul_f32 v[152:153], v[152:153], v[158:159]
	v_fma_f32 v157, v86, v157, v102
	v_add_f32_e32 v153, v153, v157
	v_add_f32_e32 v153, v152, v153
	v_mul_f32_e32 v152, 0xbfb8aa3b, v153
	v_exp_f32_e32 v157, v152
	v_add_f32_e32 v158, 1.0, v161
	v_rcp_f32_e32 v158, v158
	v_mul_f32_e32 v159, v143, v160
	v_add_f32_e32 v157, 1.0, v157
	v_rcp_f32_e32 v157, v157
	v_mul_f32_e32 v158, v159, v158
	v_mul_f32_e32 v153, v142, v153
	v_mov_b32_e32 v160, v133
	v_mul_f32_e32 v153, v153, v157
	v_cvt_pk_bf16_f32 v158, v153, v158
	v_cvt_pk_bf16_f32 v159, v151, v162
	v_cvt_pk_bf16_f32 v151, v138, v139
	v_mov_b32_e32 v161, v81
	v_cvt_pk_bf16_f32 v151, v140, v141
	v_cvt_pk_bf16_f32 v142, v142, v143
	v_cndmask_b32_e64 v143, v130, v146, s[8:9]
	v_cvt_pk_bf16_f32 v142, v144, v145
	s_nop 1
	v_mov_b32_dpp v151, v143 row_ror:2 row_mask:0xf bank_mask:0xf
	v_cndmask_b32_e64 v142, v130, v146, s[6:7]
	s_nop 1
	v_mov_b32_dpp v145, v142 row_ror:1 row_mask:0xf bank_mask:0xf
	v_cndmask_b32_e64 v142, v131, v147, s[6:7]
	v_cndmask_b32_e64 v143, v131, v147, s[8:9]
	s_nop 1
	v_mov_b32_dpp v147, v142 row_ror:1 row_mask:0xf bank_mask:0xf
	v_cndmask_b32_e64 v142, v132, v148, s[6:7]
	v_mov_b32_dpp v144, v143 row_ror:2 row_mask:0xf bank_mask:0xf
	v_cndmask_b32_e64 v146, v132, v148, s[8:9]
	v_mov_b32_dpp v143, v142 row_ror:1 row_mask:0xf bank_mask:0xf
	v_cndmask_b32_e64 v142, v133, v149, s[6:7]
	v_cndmask_b32_e64 v148, v133, v149, s[8:9]
	s_nop 1
	v_mov_b32_dpp v149, v142 row_ror:1 row_mask:0xf bank_mask:0xf
	v_mov_b32_dpp v142, v148 row_ror:2 row_mask:0xf bank_mask:0xf
	v_mov_b32_e32 v148, v77
	v_mov_b32_dpp v146, v146 row_ror:2 row_mask:0xf bank_mask:0xf
	v_fma_f32 v144, v67, v144, v71
	v_pk_mul_f32 v[148:149], v[160:161], v[148:149]
	v_fma_f32 v142, v69, v142, v73
	v_add_f32_e32 v142, v149, v142
	v_add_f32_e32 v153, v148, v142
	v_mul_f32_e32 v142, 0xbfb8aa3b, v153
	v_exp_f32_e32 v157, v142
	v_mov_b32_e32 v148, v132
	v_mov_b32_e32 v149, v80
	v_mov_b32_e32 v142, v76
	v_pk_mul_f32 v[142:143], v[148:149], v[142:143]
	v_fma_f32 v146, v68, v146, v72
	v_add_f32_e32 v143, v143, v146
	v_add_f32_e32 v143, v142, v143
	v_mul_f32_e32 v142, 0xbfb8aa3b, v143
	v_exp_f32_e32 v146, v142
	v_add_f32_e32 v148, 1.0, v157
	v_rcp_f32_e32 v148, v148
	v_mul_f32_e32 v149, v137, v153
	v_add_f32_e32 v146, 1.0, v146
	v_rcp_f32_e32 v146, v146
	v_mul_f32_e32 v143, v136, v143
	v_mul_f32_e32 v153, v149, v148
	v_mov_b32_e32 v148, v131
	v_mul_f32_e32 v143, v143, v146
	v_mov_b32_e32 v149, v79
	v_mov_b32_e32 v146, v75
	v_pk_mul_f32 v[146:147], v[148:149], v[146:147]
	v_mov_b32_e32 v150, v93
	v_add_f32_e32 v144, v147, v144
	v_add_f32_e32 v148, v146, v144
	v_mul_f32_e32 v144, 0xbfb8aa3b, v148
	v_exp_f32_e32 v149, v144
	v_mov_b32_e32 v146, v130
	v_mov_b32_e32 v147, v78
	v_mov_b32_e32 v144, v74
	v_pk_mul_f32 v[144:145], v[146:147], v[144:145]
	v_fma_f32 v146, v66, v151, v70
	v_add_f32_e32 v145, v145, v146
	v_add_f32_e32 v145, v144, v145
	v_mul_f32_e32 v144, 0xbfb8aa3b, v145
	v_exp_f32_e32 v146, v144
	v_add_f32_e32 v147, 1.0, v149
	v_rcp_f32_e32 v147, v147
	v_mul_f32_e32 v145, v134, v145
	v_add_f32_e32 v146, 1.0, v146
	v_rcp_f32_e32 v146, v146
	v_mul_f32_e32 v148, v135, v148
	v_mul_f32_e32 v147, v148, v147
	v_mov_b32_e32 v148, v125
	v_mul_f32_e32 v145, v145, v146
	v_cvt_pk_bf16_f32 v160, v145, v147
	v_cndmask_b32_e64 v145, v125, v141, s[6:7]
; __device__ __forceinline__ unsigned cvt_pk_bf16(float lo, float hi) { unsigned r; asm volatile("v_cvt_pk_bf16_f32 %0, %1, %2" : "=v"(r) : "v"(lo), "v"(hi)); return r; }
;     __device__ __forceinline__ void operator()(const f32x4 (&acc)[2][2][4][2], const Unit& u, int wr, int wc, int fr, int fq) const {
;     ...
;                 for (int n = 0; n < 2; ++n) {
;                     const f32x4 g = acc[ai][0][m][n], uu = acc[ai][1][m][n], gp = acc[ai][0][m > 0 ? m - 1 : 0][n];
;                     f32x4 r;
; #pragma unroll
;                     for (int e = 0; e < 4; ++e) {
;                         const float s1 = (fr == 15) ? gp[e] : g[e], s2 = (fr >= 14) ? gp[e] : g[e];
;                         const float p1 = __int_as_float(__builtin_amdgcn_ds_bpermute(src1, __float_as_int(s1))), p2 = __int_as_float(__builtin_amdgcn_ds_bpermute(src2, __float_as_int(s2)));
;                         const float c = bb[n][e] + w0[n][e] * p2 + w1[n][e] * p1 + w2[n][e] * g[e];
;                         r[e] = c * uu[e] * __builtin_amdgcn_rcpf(1.0f + __builtin_amdgcn_exp2f(c * -1.4426950408889634f));
;                     }
;                     if (n == 0) { wa.x = cvt_pk_bf16(r[0], r[1]); wa.y = cvt_pk_bf16(r[2], r[3]); wg.x = cvt_pk_bf16(g[0], g[1]); wg.y = cvt_pk_bf16(g[2], g[3]); wu.x = cvt_pk_bf16(uu[0], uu[1]); wu.y = cvt_pk_bf16(uu[2], uu[3]); }
;                     else { wa.z = cvt_pk_bf16(r[0], r[1]); wa.w = cvt_pk_bf16(r[2], r[3]); wg.z = cvt_pk_bf16(g[0], g[1]); wg.w = cvt_pk_bf16(g[2], g[3]); wu.z = cvt_pk_bf16(uu[0], uu[1]); wu.w = cvt_pk_bf16(uu[2], uu[3]); }
;                 }
;                 if (m == 0 && fr < 2) {
;                     *(u32x4*)(hg + (size_t)(blk * 4 + 2 + fr) * dff + f0) = wg; *(u32x4*)(hu + (size_t)(blk * 2 + fr) * dff + f0) = wu;
;                 } else {
;                     *(u32x4*)(act + (size_t)(rowb + m * 16 + fr) * dff + f0) = wa;
	v_cndmask_b32_e64 v141, v125, v141, s[8:9]
	s_nop 1
	v_mov_b32_dpp v147, v145 row_ror:1 row_mask:0xf bank_mask:0xf
	v_mov_b32_dpp v141, v141 row_ror:2 row_mask:0xf bank_mask:0xf
	v_cvt_pk_bf16_f32 v161, v143, v153
	v_cvt_pk_bf16_f32 v143, v130, v131
	v_mov_b32_e32 v149, v97
	v_cvt_pk_bf16_f32 v143, v132, v133
	v_cvt_pk_bf16_f32 v134, v134, v135
	v_mov_b32_e32 v146, v93
	v_cvt_pk_bf16_f32 v134, v136, v137
	v_or_b32_e32 v136, 16, v156
	v_mov_b64_e32 v[134:135], s[22:23]
	v_mad_i64_i32 v[136:137], s[16:17], v136, s78, v[134:135]
	v_pk_mul_f32 v[146:147], v[148:149], v[146:147]
	v_fma_f32 v141, v89, v141, v105
	v_lshl_add_u64 v[136:137], v[136:137], 0, v[154:155]
	v_add_f32_e32 v141, v147, v141
	global_store_dwordx4 v[136:137], v[158:161], off
	v_cndmask_b32_e64 v136, v122, v138, s[6:7]
	v_cndmask_b32_e64 v138, v122, v138, s[8:9]
	v_add_f32_e32 v145, v146, v141
	v_mov_b32_dpp v137, v136 row_ror:1 row_mask:0xf bank_mask:0xf
	v_mov_b32_dpp v143, v138 row_ror:2 row_mask:0xf bank_mask:0xf
	v_cndmask_b32_e64 v136, v123, v139, s[6:7]
	v_cndmask_b32_e64 v138, v123, v139, s[8:9]
	v_mul_f32_e32 v141, 0xbfb8aa3b, v145
	v_mov_b32_dpp v139, v136 row_ror:1 row_mask:0xf bank_mask:0xf
	v_mov_b32_dpp v136, v138 row_ror:2 row_mask:0xf bank_mask:0xf
	v_cndmask_b32_e64 v138, v124, v140, s[6:7]
	v_exp_f32_e32 v146, v141
	v_cndmask_b32_e64 v140, v124, v140, s[8:9]
	v_mov_b32_dpp v141, v138 row_ror:1 row_mask:0xf bank_mask:0xf
	s_nop 1
	v_mov_b32_dpp v138, v140 row_ror:2 row_mask:0xf bank_mask:0xf
	v_add_f32_e32 v140, 1.0, v146
	v_rcp_f32_e32 v148, v140
	v_mov_b32_e32 v146, v124
	v_mov_b32_e32 v147, v96
	v_mov_b32_e32 v140, v92
	v_pk_mul_f32 v[140:141], v[146:147], v[140:141]
	v_fma_f32 v138, v88, v138, v104
	v_add_f32_e32 v138, v141, v138
	v_add_f32_e32 v138, v140, v138
	v_mul_f32_e32 v140, 0xbfb8aa3b, v138
	v_exp_f32_e32 v140, v140
	v_mul_f32_e32 v141, v129, v145
	v_mul_f32_e32 v146, v128, v138
	v_mul_f32_e32 v145, v141, v148
	v_add_f32_e32 v138, 1.0, v140
	v_rcp_f32_e32 v147, v138
	v_mov_b32_e32 v140, v123
	v_mov_b32_e32 v141, v95
	v_mov_b32_e32 v138, v91
	v_pk_mul_f32 v[138:139], v[140:141], v[138:139]
	v_fma_f32 v136, v87, v136, v103
	v_add_f32_e32 v136, v139, v136
	v_add_f32_e32 v140, v138, v136
	v_mul_f32_e32 v136, 0xbfb8aa3b, v140
	v_exp_f32_e32 v141, v136
	v_mov_b32_e32 v138, v122
	v_mov_b32_e32 v139, v94
	v_mov_b32_e32 v136, v90
	v_pk_mul_f32 v[136:137], v[138:139], v[136:137]
	v_fma_f32 v138, v86, v143, v102
	v_add_f32_e32 v137, v137, v138
	v_add_f32_e32 v136, v136, v137
	v_mul_f32_e32 v137, 0xbfb8aa3b, v136
	v_exp_f32_e32 v137, v137
	v_add_f32_e32 v139, 1.0, v141
	v_rcp_f32_e32 v139, v139
	v_mul_f32_e32 v136, v126, v136
	v_add_f32_e32 v137, 1.0, v137
	v_rcp_f32_e32 v137, v137
	v_mul_f32_e32 v138, v146, v147
	v_mul_f32_e32 v140, v127, v140
	v_mul_f32_e32 v139, v140, v139
	v_mul_f32_e32 v136, v136, v137
	v_cvt_pk_bf16_f32 v136, v136, v139
	v_cvt_pk_bf16_f32 v137, v138, v145
	v_cvt_pk_bf16_f32 v138, v122, v123
	v_mov_b32_e32 v139, v81
	v_cvt_pk_bf16_f32 v138, v124, v125
	v_cvt_pk_bf16_f32 v126, v126, v127
	v_mov_b32_e32 v152, v91
	v_cvt_pk_bf16_f32 v126, v128, v129
	v_cndmask_b32_e64 v128, v110, v130, s[8:9]
	v_cndmask_b32_e64 v126, v110, v130, s[6:7]
	v_cndmask_b32_e64 v130, v113, v133, s[6:7]
	v_cndmask_b32_e64 v133, v113, v133, s[8:9]
	v_mov_b32_dpp v127, v126 row_ror:1 row_mask:0xf bank_mask:0xf
	v_mov_b32_dpp v140, v128 row_ror:2 row_mask:0xf bank_mask:0xf
	v_cndmask_b32_e64 v126, v111, v131, s[6:7]
	v_cndmask_b32_e64 v128, v111, v131, s[8:9]
	v_mov_b32_dpp v131, v130 row_ror:1 row_mask:0xf bank_mask:0xf
	v_mov_b32_dpp v133, v133 row_ror:2 row_mask:0xf bank_mask:0xf
	v_mov_b32_e32 v138, v113
	v_mov_b32_e32 v130, v77
	v_mov_b32_dpp v129, v126 row_ror:1 row_mask:0xf bank_mask:0xf
	v_pk_mul_f32 v[130:131], v[138:139], v[130:131]
	v_fma_f32 v133, v69, v133, v73
	v_add_f32_e32 v131, v131, v133
	v_add_f32_e32 v138, v130, v131
	v_mul_f32_e32 v130, 0xbfb8aa3b, v138
	v_mov_b32_dpp v126, v128 row_ror:2 row_mask:0xf bank_mask:0xf
	v_cndmask_b32_e64 v128, v112, v132, s[6:7]
	v_exp_f32_e32 v130, v130
	v_cndmask_b32_e64 v132, v112, v132, s[8:9]
	v_mov_b32_dpp v131, v128 row_ror:1 row_mask:0xf bank_mask:0xf
	s_nop 1
	v_mov_b32_dpp v128, v132 row_ror:2 row_mask:0xf bank_mask:0xf
	v_add_f32_e32 v130, 1.0, v130
	v_rcp_f32_e32 v139, v130
	v_mov_b32_e32 v132, v112
	v_mov_b32_e32 v133, v80
	v_mov_b32_e32 v130, v76
	v_pk_mul_f32 v[130:131], v[132:133], v[130:131]
	v_fma_f32 v128, v68, v128, v72
	v_add_f32_e32 v128, v131, v128
	v_add_f32_e32 v128, v130, v128
	v_mul_f32_e32 v130, 0xbfb8aa3b, v128
	v_exp_f32_e32 v130, v130
	v_mul_f32_e32 v131, v121, v138
	v_mul_f32_e32 v133, v120, v128
	v_mul_f32_e32 v132, v131, v139
	v_add_f32_e32 v128, 1.0, v130
	v_rcp_f32_e32 v138, v128
	v_mov_b32_e32 v130, v111
	v_mov_b32_e32 v131, v79
	v_mov_b32_e32 v128, v75
	v_pk_mul_f32 v[128:129], v[130:131], v[128:129]
	v_fma_f32 v126, v67, v126, v71
	v_add_f32_e32 v126, v129, v126
	v_add_f32_e32 v130, v128, v126
	v_mul_f32_e32 v126, 0xbfb8aa3b, v130
	v_exp_f32_e32 v131, v126
	v_mov_b32_e32 v128, v110
	v_mov_b32_e32 v129, v78
	v_mov_b32_e32 v126, v74
	v_pk_mul_f32 v[126:127], v[128:129], v[126:127]
	v_fma_f32 v128, v66, v140, v70
	v_add_f32_e32 v127, v127, v128
	v_add_f32_e32 v126, v126, v127
	v_mul_f32_e32 v127, 0xbfb8aa3b, v126
	v_exp_f32_e32 v127, v127
	v_add_f32_e32 v129, 1.0, v131
	v_rcp_f32_e32 v129, v129
	v_mul_f32_e32 v126, v118, v126
	v_add_f32_e32 v127, 1.0, v127
	v_rcp_f32_e32 v127, v127
	v_mul_f32_e32 v130, v119, v130
	v_mul_f32_e32 v128, v133, v138
	v_mul_f32_e32 v129, v130, v129
	v_mul_f32_e32 v126, v126, v127
	v_cvt_pk_bf16_f32 v138, v126, v129
	v_cvt_pk_bf16_f32 v139, v128, v132
; __device__ __forceinline__ unsigned cvt_pk_bf16(float lo, float hi) { unsigned r; asm volatile("v_cvt_pk_bf16_f32 %0, %1, %2" : "=v"(r) : "v"(lo), "v"(hi)); return r; }
;     __device__ __forceinline__ void operator()(const f32x4 (&acc)[2][2][4][2], const Unit& u, int wr, int wc, int fr, int fq) const {
;     ...
;                 for (int n = 0; n < 2; ++n) {
;                     const f32x4 g = acc[ai][0][m][n], uu = acc[ai][1][m][n], gp = acc[ai][0][m > 0 ? m - 1 : 0][n];
;                     f32x4 r;
; #pragma unroll
;                     for (int e = 0; e < 4; ++e) {
;                         const float s1 = (fr == 15) ? gp[e] : g[e], s2 = (fr >= 14) ? gp[e] : g[e];
;                         const float p1 = __int_as_float(__builtin_amdgcn_ds_bpermute(src1, __float_as_int(s1))), p2 = __int_as_float(__builtin_amdgcn_ds_bpermute(src2, __float_as_int(s2)));
;                         const float c = bb[n][e] + w0[n][e] * p2 + w1[n][e] * p1 + w2[n][e] * g[e];
;                         r[e] = c * uu[e] * __builtin_amdgcn_rcpf(1.0f + __builtin_amdgcn_exp2f(c * -1.4426950408889634f));
;                     }
;                     if (n == 0) { wa.x = cvt_pk_bf16(r[0], r[1]); wa.y = cvt_pk_bf16(r[2], r[3]); wg.x = cvt_pk_bf16(g[0], g[1]); wg.y = cvt_pk_bf16(g[2], g[3]); wu.x = cvt_pk_bf16(uu[0], uu[1]); wu.y = cvt_pk_bf16(uu[2], uu[3]); }
;                     else { wa.z = cvt_pk_bf16(r[0], r[1]); wa.w = cvt_pk_bf16(r[2], r[3]); wg.z = cvt_pk_bf16(g[0], g[1]); wg.w = cvt_pk_bf16(g[2], g[3]); wu.z = cvt_pk_bf16(uu[0], uu[1]); wu.w = cvt_pk_bf16(uu[2], uu[3]); }
;                 }
;                 if (m == 0 && fr < 2) {
;                     *(u32x4*)(hg + (size_t)(blk * 4 + 2 + fr) * dff + f0) = wg; *(u32x4*)(hu + (size_t)(blk * 2 + fr) * dff + f0) = wu;
;                 } else {
;                     *(u32x4*)(act + (size_t)(rowb + m * 16 + fr) * dff + f0) = wa;
;                 }
;                 if (m == 3 && fr >= 14) *(u32x4*)(hg + (size_t)(blk * 4 + fr - 14) * dff + f0) = wg;
	v_cvt_pk_bf16_f32 v126, v110, v111
	v_mov_b32_e32 v127, v97
	v_cvt_pk_bf16_f32 v126, v112, v113
	v_cvt_pk_bf16_f32 v118, v118, v119
	v_mov_b32_e32 v142, v77
	v_cvt_pk_bf16_f32 v118, v120, v121
	v_cndmask_b32_e64 v120, v114, v122, s[8:9]
	v_or_b32_e32 v118, 32, v156
	v_mad_i64_i32 v[118:119], s[16:17], v118, s78, v[134:135]
	v_lshl_add_u64 v[118:119], v[118:119], 0, v[154:155]
	global_store_dwordx4 v[118:119], v[136:139], off
	v_cndmask_b32_e64 v118, v114, v122, s[6:7]
	v_cndmask_b32_e64 v122, v117, v125, s[6:7]
	v_cndmask_b32_e64 v125, v117, v125, s[8:9]
	v_mov_b32_dpp v119, v118 row_ror:1 row_mask:0xf bank_mask:0xf
	v_mov_b32_dpp v128, v120 row_ror:2 row_mask:0xf bank_mask:0xf
	v_cndmask_b32_e64 v118, v115, v123, s[6:7]
	v_cndmask_b32_e64 v120, v115, v123, s[8:9]
	v_mov_b32_dpp v123, v122 row_ror:1 row_mask:0xf bank_mask:0xf
	v_mov_b32_dpp v125, v125 row_ror:2 row_mask:0xf bank_mask:0xf
	v_mov_b32_e32 v126, v117
	v_mov_b32_e32 v122, v93
	v_mov_b32_dpp v121, v118 row_ror:1 row_mask:0xf bank_mask:0xf
	v_pk_mul_f32 v[122:123], v[126:127], v[122:123]
	v_fma_f32 v125, v89, v125, v105
	v_add_f32_e32 v123, v123, v125
	v_add_f32_e32 v126, v122, v123
	v_mul_f32_e32 v122, 0xbfb8aa3b, v126
	v_mov_b32_dpp v118, v120 row_ror:2 row_mask:0xf bank_mask:0xf
	v_cndmask_b32_e64 v120, v116, v124, s[6:7]
	v_exp_f32_e32 v122, v122
	v_cndmask_b32_e64 v124, v116, v124, s[8:9]
	v_mov_b32_dpp v123, v120 row_ror:1 row_mask:0xf bank_mask:0xf
	s_nop 1
	v_mov_b32_dpp v120, v124 row_ror:2 row_mask:0xf bank_mask:0xf
	v_add_f32_e32 v122, 1.0, v122
	v_rcp_f32_e32 v127, v122
	v_mov_b32_e32 v124, v116
	v_mov_b32_e32 v125, v96
	v_mov_b32_e32 v122, v92
	v_pk_mul_f32 v[122:123], v[124:125], v[122:123]
	v_fma_f32 v120, v88, v120, v104
	v_add_f32_e32 v120, v123, v120
	v_add_f32_e32 v120, v122, v120
	v_mul_f32_e32 v122, 0xbfb8aa3b, v120
	v_exp_f32_e32 v122, v122
	v_mul_f32_e32 v123, v109, v126
	v_mul_f32_e32 v125, v108, v120
	v_mul_f32_e32 v124, v123, v127
	v_add_f32_e32 v120, 1.0, v122
	v_rcp_f32_e32 v126, v120
	v_mov_b32_e32 v122, v115
	v_mov_b32_e32 v123, v95
	v_mov_b32_e32 v120, v91
	v_pk_mul_f32 v[120:121], v[122:123], v[120:121]
	v_fma_f32 v118, v87, v118, v103
	v_add_f32_e32 v118, v121, v118
	v_add_f32_e32 v122, v120, v118
	v_mul_f32_e32 v118, 0xbfb8aa3b, v122
	v_exp_f32_e32 v123, v118
	v_mov_b32_e32 v120, v114
	v_mov_b32_e32 v121, v94
	v_mov_b32_e32 v118, v90
	v_pk_mul_f32 v[118:119], v[120:121], v[118:119]
	v_fma_f32 v120, v86, v128, v102
	v_add_f32_e32 v119, v119, v120
	v_add_f32_e32 v118, v118, v119
	v_mul_f32_e32 v119, 0xbfb8aa3b, v118
	v_exp_f32_e32 v119, v119
	v_add_f32_e32 v121, 1.0, v123
	v_rcp_f32_e32 v121, v121
	v_mul_f32_e32 v118, v106, v118
	v_add_f32_e32 v119, 1.0, v119
	v_rcp_f32_e32 v119, v119
	v_mul_f32_e32 v122, v107, v122
	v_mul_f32_e32 v120, v125, v126
	v_mul_f32_e32 v121, v122, v121
	v_mul_f32_e32 v118, v118, v119
	v_cvt_pk_bf16_f32 v118, v118, v121
	v_cvt_pk_bf16_f32 v119, v120, v124
	v_cvt_pk_bf16_f32 v114, v114, v115
	v_cvt_pk_bf16_f32 v115, v116, v117
	v_cvt_pk_bf16_f32 v106, v106, v107
	v_mov_b32_e32 v116, v101
	v_cvt_pk_bf16_f32 v106, v108, v109
	v_cndmask_b32_e64 v108, v98, v110, s[8:9]
	v_cndmask_b32_e64 v106, v98, v110, s[6:7]
	v_cndmask_b32_e64 v110, v101, v113, s[6:7]
	v_cndmask_b32_e64 v113, v101, v113, s[8:9]
	v_mov_b32_dpp v107, v106 row_ror:1 row_mask:0xf bank_mask:0xf
	v_mov_b32_dpp v120, v108 row_ror:2 row_mask:0xf bank_mask:0xf
	v_cndmask_b32_e64 v106, v99, v111, s[6:7]
	v_cndmask_b32_e64 v108, v99, v111, s[8:9]
	v_mov_b32_dpp v111, v110 row_ror:1 row_mask:0xf bank_mask:0xf
	v_mov_b32_dpp v113, v113 row_ror:2 row_mask:0xf bank_mask:0xf
	v_mov_b32_e32 v117, v81
	v_mov_b32_e32 v110, v77
	v_mov_b32_dpp v109, v106 row_ror:1 row_mask:0xf bank_mask:0xf
	v_pk_mul_f32 v[110:111], v[116:117], v[110:111]
	v_fma_f32 v113, v69, v113, v73
	v_add_f32_e32 v111, v111, v113
	v_add_f32_e32 v116, v110, v111
	v_mul_f32_e32 v110, 0xbfb8aa3b, v116
	v_mov_b32_dpp v106, v108 row_ror:2 row_mask:0xf bank_mask:0xf
	v_cndmask_b32_e64 v108, v100, v112, s[6:7]
	v_exp_f32_e32 v110, v110
	v_cndmask_b32_e64 v112, v100, v112, s[8:9]
	v_mov_b32_dpp v111, v108 row_ror:1 row_mask:0xf bank_mask:0xf
	s_nop 1
	v_mov_b32_dpp v108, v112 row_ror:2 row_mask:0xf bank_mask:0xf
	v_add_f32_e32 v110, 1.0, v110
	v_rcp_f32_e32 v117, v110
	v_mov_b32_e32 v112, v100
	v_mov_b32_e32 v113, v80
	v_mov_b32_e32 v110, v76
	v_pk_mul_f32 v[110:111], v[112:113], v[110:111]
	v_fma_f32 v108, v68, v108, v72
	v_add_f32_e32 v108, v111, v108
	v_add_f32_e32 v108, v110, v108
	v_mul_f32_e32 v110, 0xbfb8aa3b, v108
	v_exp_f32_e32 v110, v110
	v_mul_f32_e32 v111, v85, v116
	v_mul_f32_e32 v113, v84, v108
	v_mul_f32_e32 v112, v111, v117
	v_add_f32_e32 v108, 1.0, v110
	v_rcp_f32_e32 v116, v108
	v_mov_b32_e32 v110, v99
	v_mov_b32_e32 v111, v79
	v_mov_b32_e32 v108, v75
	v_pk_mul_f32 v[108:109], v[110:111], v[108:109]
	v_fma_f32 v106, v67, v106, v71
	v_add_f32_e32 v106, v109, v106
	v_add_f32_e32 v110, v108, v106
	v_mul_f32_e32 v106, 0xbfb8aa3b, v110
	v_exp_f32_e32 v111, v106
	v_mov_b32_e32 v108, v98
	v_mov_b32_e32 v109, v78
	v_mov_b32_e32 v106, v74
	v_pk_mul_f32 v[106:107], v[108:109], v[106:107]
	v_fma_f32 v108, v66, v120, v70
	v_add_f32_e32 v107, v107, v108
	v_add_f32_e32 v106, v106, v107
	v_mul_f32_e32 v107, 0xbfb8aa3b, v106
	v_exp_f32_e32 v107, v107
	v_add_f32_e32 v109, 1.0, v111
	v_rcp_f32_e32 v109, v109
	v_mul_f32_e32 v110, v83, v110
	v_add_f32_e32 v107, 1.0, v107
	v_rcp_f32_e32 v107, v107
	v_mul_f32_e32 v106, v82, v106
	v_mul_f32_e32 v108, v113, v116
	v_mul_f32_e32 v109, v110, v109
	v_mul_f32_e32 v106, v106, v107
	v_cvt_pk_bf16_f32 v120, v106, v109
	v_cvt_pk_bf16_f32 v121, v108, v112
	v_cvt_pk_bf16_f32 v116, v98, v99
	v_cvt_pk_bf16_f32 v117, v100, v101
	v_cvt_pk_bf16_f32 v82, v82, v83
	v_mov_b32_e32 v144, v75
	v_cvt_pk_bf16_f32 v82, v84, v85
	s_nop 0
	v_or_b32_e32 v82, 48, v156
	v_mad_i64_i32 v[82:83], s[16:17], v82, s78, v[134:135]
	v_lshl_add_u64 v[82:83], v[82:83], 0, v[154:155]
	global_store_dwordx4 v[82:83], v[118:121], off
	s_and_saveexec_b64 s[56:57], s[8:9]
	s_cbranch_execz .LBB0_488
	v_add_u32_e32 v84, s47, v214
	v_mov_b64_e32 v[82:83], s[28:29]
	v_mad_i64_i32 v[82:83], s[16:17], v84, s78, v[82:83]
	v_lshl_add_u64 v[82:83], v[196:197], 1, v[82:83]
	global_store_dwordx4 v[82:83], v[114:117], off
; __device__ __forceinline__ unsigned cvt_pk_bf16(float lo, float hi) { unsigned r; asm volatile("v_cvt_pk_bf16_f32 %0, %1, %2" : "=v"(r) : "v"(lo), "v"(hi)); return r; }
;     __device__ __forceinline__ void operator()(const f32x4 (&acc)[2][2][4][2], const Unit& u, int wr, int wc, int fr, int fq) const {
;     ...
;             const int rowb = u.pm * BM + ai * HALF + wr * 64, blk = rowb >> 6;
; #pragma unroll
;             for (int m = 0; m < 4; ++m) {
;                 u32x4 wa, wg, wu;
; #pragma unroll
;                 for (int n = 0; n < 2; ++n) {
;                     const f32x4 g = acc[ai][0][m][n], uu = acc[ai][1][m][n], gp = acc[ai][0][m > 0 ? m - 1 : 0][n];
;                     f32x4 r;
; #pragma unroll
;                     for (int e = 0; e < 4; ++e) {
;                         const float s1 = (fr == 15) ? gp[e] : g[e], s2 = (fr >= 14) ? gp[e] : g[e];
;                         const float p1 = __int_as_float(__builtin_amdgcn_ds_bpermute(src1, __float_as_int(s1))), p2 = __int_as_float(__builtin_amdgcn_ds_bpermute(src2, __float_as_int(s2)));
;                         const float c = bb[n][e] + w0[n][e] * p2 + w1[n][e] * p1 + w2[n][e] * g[e];
;                         r[e] = c * uu[e] * __builtin_amdgcn_rcpf(1.0f + __builtin_amdgcn_exp2f(c * -1.4426950408889634f));
;                     }
;                     if (n == 0) { wa.x = cvt_pk_bf16(r[0], r[1]); wa.y = cvt_pk_bf16(r[2], r[3]); wg.x = cvt_pk_bf16(g[0], g[1]); wg.y = cvt_pk_bf16(g[2], g[3]); wu.x = cvt_pk_bf16(uu[0], uu[1]); wu.y = cvt_pk_bf16(uu[2], uu[3]); }
;                     else { wa.z = cvt_pk_bf16(r[0], r[1]); wa.w = cvt_pk_bf16(r[2], r[3]); wg.z = cvt_pk_bf16(g[0], g[1]); wg.w = cvt_pk_bf16(g[2], g[3]); wu.z = cvt_pk_bf16(uu[0], uu[1]); wu.w = cvt_pk_bf16(uu[2], uu[3]); }
;                 }
;                 if (m == 0 && fr < 2) {
;                     *(u32x4*)(hg + (size_t)(blk * 4 + 2 + fr) * dff + f0) = wg; *(u32x4*)(hu + (size_t)(blk * 2 + fr) * dff + f0) = wu;
;                 } else {
;                     *(u32x4*)(act + (size_t)(rowb + m * 16 + fr) * dff + f0) = wa;
.LBB0_488:
	s_or_b64 exec, exec, s[56:57]
	v_mov_b32_dpp v82, v57 row_ror:2 row_mask:0xf bank_mask:0xf
	v_mov_b32_dpp v83, v57 row_ror:1 row_mask:0xf bank_mask:0xf
	v_mov_b32_dpp v99, v56 row_ror:1 row_mask:0xf bank_mask:0xf
	v_mov_b32_dpp v100, v55 row_ror:2 row_mask:0xf bank_mask:0xf
	v_mov_b32_dpp v85, v54 row_ror:2 row_mask:0xf bank_mask:0xf
	v_fma_f32 v82, v89, v82, v105
	v_fmac_f32_e32 v82, v97, v83
	v_fmac_f32_e32 v82, v57, v93
	v_mov_b32_dpp v93, v56 row_ror:2 row_mask:0xf bank_mask:0xf
	v_mul_f32_e32 v83, 0xbfb8aa3b, v82
	v_exp_f32_e32 v83, v83
	v_mov_b32_dpp v98, v55 row_ror:1 row_mask:0xf bank_mask:0xf
	v_mov_b32_dpp v84, v54 row_ror:1 row_mask:0xf bank_mask:0xf
	v_fma_f32 v93, v88, v93, v104
	v_fmac_f32_e32 v93, v96, v99
	v_fmac_f32_e32 v93, v56, v92
	v_add_f32_e32 v83, 1.0, v83
	v_mul_f32_e32 v99, 0xbfb8aa3b, v93
	v_rcp_f32_e32 v83, v83
	v_exp_f32_e32 v99, v99
	v_mul_f32_e32 v82, v65, v82
	v_fma_f32 v85, v86, v85, v102
	v_mul_f32_e32 v83, v82, v83
	v_mul_f32_e32 v82, v64, v93
	v_add_f32_e32 v93, 1.0, v99
	v_fma_f32 v99, v87, v100, v103
	v_fmac_f32_e32 v99, v95, v98
	v_fmac_f32_e32 v99, v55, v91
	v_fmac_f32_e32 v85, v94, v84
	v_mul_f32_e32 v91, 0xbfb8aa3b, v99
	v_fmac_f32_e32 v85, v54, v90
	v_rcp_f32_e32 v93, v93
	v_exp_f32_e32 v91, v91
	v_mul_f32_e32 v84, 0xbfb8aa3b, v85
	v_exp_f32_e32 v84, v84
	v_mul_f32_e32 v93, v82, v93
	v_add_f32_e32 v82, 1.0, v91
	v_rcp_f32_e32 v82, v82
	v_add_f32_e32 v84, 1.0, v84
	v_rcp_f32_e32 v84, v84
	v_mul_f32_e32 v91, v63, v99
	v_mul_f32_e32 v82, v91, v82
	v_mul_f32_e32 v85, v62, v85
	v_mul_f32_e32 v84, v85, v84
	v_cvt_pk_bf16_f32 v82, v84, v82
	v_cvt_pk_bf16_f32 v83, v93, v83
	v_cvt_pk_bf16_f32 v98, v54, v55
	v_cvt_pk_bf16_f32 v99, v56, v57
	v_cvt_pk_bf16_f32 v62, v62, v63
	v_cvt_pk_bf16_f32 v63, v64, v65
	v_mov_b32_dpp v64, v53 row_ror:2 row_mask:0xf bank_mask:0xf
	v_mov_b32_dpp v65, v53 row_ror:1 row_mask:0xf bank_mask:0xf
	v_mov_b32_dpp v93, v52 row_ror:1 row_mask:0xf bank_mask:0xf
	v_mov_b32_dpp v100, v51 row_ror:2 row_mask:0xf bank_mask:0xf
	v_mov_b32_dpp v85, v50 row_ror:2 row_mask:0xf bank_mask:0xf
	v_fma_f32 v64, v69, v64, v73
	v_fmac_f32_e32 v64, v81, v65
	v_fmac_f32_e32 v64, v53, v77
	v_mov_b32_dpp v77, v52 row_ror:2 row_mask:0xf bank_mask:0xf
	v_mul_f32_e32 v65, 0xbfb8aa3b, v64
	v_exp_f32_e32 v65, v65
	v_mov_b32_dpp v91, v51 row_ror:1 row_mask:0xf bank_mask:0xf
	v_mov_b32_dpp v84, v50 row_ror:1 row_mask:0xf bank_mask:0xf
	v_fma_f32 v77, v68, v77, v72
	v_fmac_f32_e32 v77, v80, v93
	v_fmac_f32_e32 v77, v52, v76
	v_add_f32_e32 v65, 1.0, v65
	v_mul_f32_e32 v93, 0xbfb8aa3b, v77
	v_rcp_f32_e32 v65, v65
	v_exp_f32_e32 v93, v93
	v_mul_f32_e32 v64, v61, v64
	v_fma_f32 v85, v66, v85, v70
	v_mul_f32_e32 v64, v64, v65
	v_mul_f32_e32 v65, v60, v77
	v_add_f32_e32 v77, 1.0, v93
	v_fma_f32 v93, v67, v100, v71
	v_fmac_f32_e32 v93, v79, v91
	v_fmac_f32_e32 v93, v51, v75
	v_fmac_f32_e32 v85, v78, v84
	v_mul_f32_e32 v75, 0xbfb8aa3b, v93
	v_fmac_f32_e32 v85, v50, v74
	v_exp_f32_e32 v75, v75
	v_mul_f32_e32 v84, 0xbfb8aa3b, v85
	v_rcp_f32_e32 v77, v77
	v_exp_f32_e32 v84, v84
	v_add_f32_e32 v75, 1.0, v75
	v_rcp_f32_e32 v75, v75
	v_mul_f32_e32 v65, v65, v77
	v_add_f32_e32 v77, 1.0, v84
	v_rcp_f32_e32 v77, v77
	v_mul_f32_e32 v84, v59, v93
	v_mul_f32_e32 v75, v84, v75
	v_mul_f32_e32 v84, v58, v85
	v_mul_f32_e32 v77, v84, v77
	v_cvt_pk_bf16_f32 v84, v77, v75
	v_cvt_pk_bf16_f32 v85, v65, v64
	v_cvt_pk_bf16_f32 v100, v50, v51
	v_cvt_pk_bf16_f32 v101, v52, v53
	v_cvt_pk_bf16_f32 v64, v58, v59
	v_cvt_pk_bf16_f32 v65, v60, v61
	s_and_saveexec_b64 s[16:17], s[10:11]
	s_xor_b64 s[56:57], exec, s[16:17]
	s_or_saveexec_b64 s[56:57], s[56:57]
	s_add_i32 s47, s45, 0x80
	v_or_b32_e32 v60, s47, v170
	s_ashr_i32 s45, s47, 4
	v_mov_b64_e32 v[58:59], s[22:23]
	v_mov_b32_e32 v61, v60
	s_xor_b64 exec, exec, s[56:57]
	s_cbranch_execz .LBB0_492
	s_ashr_i32 s16, s47, 5
	v_or_b32_e32 v75, s45, v215
	v_mov_b64_e32 v[58:59], s[28:29]
	v_or_b32_e32 v61, s16, v170
	v_mad_i64_i32 v[58:59], s[16:17], v75, s78, v[58:59]
	v_lshl_add_u64 v[58:59], v[196:197], 1, v[58:59]
	v_mov_b64_e32 v[84:85], v[64:65]
	global_store_dwordx4 v[58:59], v[98:101], off
	v_mov_b64_e32 v[58:59], s[30:31]
	v_mov_b64_e32 v[82:83], v[62:63]
.LBB0_492:
	s_or_b64 exec, exec, s[56:57]
	v_mad_i64_i32 v[58:59], s[16:17], v61, s78, v[58:59]
	v_lshl_add_u64 v[58:59], v[58:59], 0, v[154:155]
	global_store_dwordx4 v[58:59], v[82:85], off
	v_cndmask_b32_e64 v58, v42, v54, s[6:7]
	v_cndmask_b32_e64 v54, v42, v54, s[8:9]
	s_nop 1
	v_mov_b32_dpp v91, v58 row_ror:1 row_mask:0xf bank_mask:0xf
	v_mov_b32_dpp v58, v54 row_ror:2 row_mask:0xf bank_mask:0xf
	v_cndmask_b32_e64 v54, v43, v55, s[6:7]
	v_cndmask_b32_e64 v55, v43, v55, s[8:9]
	s_nop 1
	v_mov_b32_dpp v153, v54 row_ror:1 row_mask:0xf bank_mask:0xf
	v_mov_b32_dpp v59, v55 row_ror:2 row_mask:0xf bank_mask:0xf
	v_cndmask_b32_e64 v54, v45, v57, s[6:7]
	v_cndmask_b32_e64 v55, v45, v57, s[8:9]
	s_nop 1
	v_mov_b32_dpp v151, v54 row_ror:1 row_mask:0xf bank_mask:0xf
	v_mov_b32_dpp v57, v55 row_ror:2 row_mask:0xf bank_mask:0xf
	v_mov_b32_e32 v54, v45
	v_mov_b32_e32 v55, v97
	v_cndmask_b32_e64 v61, v44, v56, s[6:7]
	v_pk_mul_f32 v[54:55], v[54:55], v[150:151]
	v_fma_f32 v57, v89, v57, v105
	v_add_f32_e32 v55, v55, v57
	v_add_f32_e32 v57, v54, v55
	v_mul_f32_e32 v54, 0xbfb8aa3b, v57
	v_exp_f32_e32 v54, v54
	v_cndmask_b32_e64 v55, v44, v56, s[8:9]
	v_mov_b32_dpp v93, v61 row_ror:1 row_mask:0xf bank_mask:0xf
	s_nop 1
	v_mov_b32_dpp v56, v55 row_ror:2 row_mask:0xf bank_mask:0xf
	v_add_f32_e32 v54, 1.0, v54
	v_rcp_f32_e32 v61, v54
	v_mov_b32_e32 v54, v44
	v_mov_b32_e32 v55, v96
	v_pk_mul_f32 v[54:55], v[54:55], v[92:93]
	v_fma_f32 v56, v88, v56, v104
; __device__ __forceinline__ unsigned cvt_pk_bf16(float lo, float hi) { unsigned r; asm volatile("v_cvt_pk_bf16_f32 %0, %1, %2" : "=v"(r) : "v"(lo), "v"(hi)); return r; }
;     __device__ __forceinline__ void operator()(const f32x4 (&acc)[2][2][4][2], const Unit& u, int wr, int wc, int fr, int fq) const {
;     ...
;                 for (int n = 0; n < 2; ++n) {
;                     const f32x4 g = acc[ai][0][m][n], uu = acc[ai][1][m][n], gp = acc[ai][0][m > 0 ? m - 1 : 0][n];
;                     f32x4 r;
; #pragma unroll
;                     for (int e = 0; e < 4; ++e) {
;                         const float s1 = (fr == 15) ? gp[e] : g[e], s2 = (fr >= 14) ? gp[e] : g[e];
;                         const float p1 = __int_as_float(__builtin_amdgcn_ds_bpermute(src1, __float_as_int(s1))), p2 = __int_as_float(__builtin_amdgcn_ds_bpermute(src2, __float_as_int(s2)));
;                         const float c = bb[n][e] + w0[n][e] * p2 + w1[n][e] * p1 + w2[n][e] * g[e];
;                         r[e] = c * uu[e] * __builtin_amdgcn_rcpf(1.0f + __builtin_amdgcn_exp2f(c * -1.4426950408889634f));
;                     }
;                     if (n == 0) { wa.x = cvt_pk_bf16(r[0], r[1]); wa.y = cvt_pk_bf16(r[2], r[3]); wg.x = cvt_pk_bf16(g[0], g[1]); wg.y = cvt_pk_bf16(g[2], g[3]); wu.x = cvt_pk_bf16(uu[0], uu[1]); wu.y = cvt_pk_bf16(uu[2], uu[3]); }
;                     else { wa.z = cvt_pk_bf16(r[0], r[1]); wa.w = cvt_pk_bf16(r[2], r[3]); wg.z = cvt_pk_bf16(g[0], g[1]); wg.w = cvt_pk_bf16(g[2], g[3]); wu.z = cvt_pk_bf16(uu[0], uu[1]); wu.w = cvt_pk_bf16(uu[2], uu[3]); }
;                 }
;                 if (m == 0 && fr < 2) {
;                     *(u32x4*)(hg + (size_t)(blk * 4 + 2 + fr) * dff + f0) = wg; *(u32x4*)(hu + (size_t)(blk * 2 + fr) * dff + f0) = wu;
;                 } else {
;                     *(u32x4*)(act + (size_t)(rowb + m * 16 + fr) * dff + f0) = wa;
	v_add_f32_e32 v55, v55, v56
	v_add_f32_e32 v54, v54, v55
	v_mul_f32_e32 v55, 0xbfb8aa3b, v54
	v_exp_f32_e32 v55, v55
	v_mul_f32_e32 v56, v49, v57
	v_mul_f32_e32 v57, v48, v54
	v_mul_f32_e32 v56, v56, v61
	v_add_f32_e32 v54, 1.0, v55
	v_rcp_f32_e32 v61, v54
	v_mov_b32_e32 v54, v43
	v_mov_b32_e32 v55, v95
	v_pk_mul_f32 v[54:55], v[54:55], v[152:153]
	v_fma_f32 v59, v87, v59, v103
	v_add_f32_e32 v55, v55, v59
	v_add_f32_e32 v59, v54, v55
	v_mul_f32_e32 v54, 0xbfb8aa3b, v59
	v_exp_f32_e32 v62, v54
	v_mov_b32_e32 v54, v42
	v_mov_b32_e32 v55, v94
	v_pk_mul_f32 v[54:55], v[54:55], v[90:91]
	v_fma_f32 v58, v86, v58, v102
	v_add_f32_e32 v55, v55, v58
	v_add_f32_e32 v54, v54, v55
	v_mul_f32_e32 v55, 0xbfb8aa3b, v54
	v_exp_f32_e32 v55, v55
	v_add_f32_e32 v58, 1.0, v62
	v_rcp_f32_e32 v58, v58
	v_mul_f32_e32 v54, v46, v54
	v_add_f32_e32 v55, 1.0, v55
	v_rcp_f32_e32 v55, v55
	v_mul_f32_e32 v59, v47, v59
	v_mul_f32_e32 v57, v57, v61
	v_mul_f32_e32 v58, v59, v58
	v_mul_f32_e32 v54, v54, v55
	v_cvt_pk_bf16_f32 v54, v54, v58
	v_cvt_pk_bf16_f32 v55, v57, v56
	v_cvt_pk_bf16_f32 v56, v42, v43
	s_nop 0
	v_cvt_pk_bf16_f32 v56, v44, v45
	v_cvt_pk_bf16_f32 v46, v46, v47
	v_cndmask_b32_e64 v47, v34, v50, s[8:9]
	v_cvt_pk_bf16_f32 v46, v48, v49
	s_nop 1
	v_mov_b32_dpp v48, v47 row_ror:2 row_mask:0xf bank_mask:0xf
	v_cndmask_b32_e64 v46, v34, v50, s[6:7]
	s_nop 1
	v_mov_b32_dpp v75, v46 row_ror:1 row_mask:0xf bank_mask:0xf
	v_cndmask_b32_e64 v46, v35, v51, s[6:7]
	v_cndmask_b32_e64 v47, v35, v51, s[8:9]
	s_nop 1
	v_mov_b32_dpp v145, v46 row_ror:1 row_mask:0xf bank_mask:0xf
	v_mov_b32_dpp v49, v47 row_ror:2 row_mask:0xf bank_mask:0xf
	v_cndmask_b32_e64 v46, v37, v53, s[6:7]
	v_cndmask_b32_e64 v47, v37, v53, s[8:9]
	s_nop 1
	v_mov_b32_dpp v143, v46 row_ror:1 row_mask:0xf bank_mask:0xf
	v_mov_b32_dpp v50, v47 row_ror:2 row_mask:0xf bank_mask:0xf
	v_mov_b32_e32 v46, v37
	v_mov_b32_e32 v47, v81
	v_cndmask_b32_e64 v51, v36, v52, s[6:7]
	v_pk_mul_f32 v[46:47], v[46:47], v[142:143]
	v_fma_f32 v50, v69, v50, v73
	v_add_f32_e32 v47, v47, v50
	v_add_f32_e32 v50, v46, v47
	v_mul_f32_e32 v46, 0xbfb8aa3b, v50
	v_exp_f32_e32 v46, v46
	v_cndmask_b32_e64 v47, v36, v52, s[8:9]
	v_mov_b32_dpp v77, v51 row_ror:1 row_mask:0xf bank_mask:0xf
	s_nop 1
	v_mov_b32_dpp v51, v47 row_ror:2 row_mask:0xf bank_mask:0xf
	v_add_f32_e32 v46, 1.0, v46
	v_rcp_f32_e32 v52, v46
	v_mov_b32_e32 v46, v36
	v_mov_b32_e32 v47, v80
	v_pk_mul_f32 v[46:47], v[46:47], v[76:77]
	v_fma_f32 v51, v68, v51, v72
	v_add_f32_e32 v47, v47, v51
	v_add_f32_e32 v46, v46, v47
	v_mul_f32_e32 v47, 0xbfb8aa3b, v46
	v_exp_f32_e32 v47, v47
	v_mul_f32_e32 v50, v41, v50
	v_mul_f32_e32 v51, v40, v46
	v_mul_f32_e32 v50, v50, v52
	v_add_f32_e32 v46, 1.0, v47
	v_rcp_f32_e32 v52, v46
	v_mov_b32_e32 v46, v35
	v_mov_b32_e32 v47, v79
	v_pk_mul_f32 v[46:47], v[46:47], v[144:145]
	v_fma_f32 v49, v67, v49, v71
	v_add_f32_e32 v47, v47, v49
	v_add_f32_e32 v49, v46, v47
	v_mul_f32_e32 v46, 0xbfb8aa3b, v49
	v_exp_f32_e32 v53, v46
	v_mov_b32_e32 v46, v34
	v_mov_b32_e32 v47, v78
	v_pk_mul_f32 v[46:47], v[46:47], v[74:75]
	v_fma_f32 v48, v66, v48, v70
	v_add_f32_e32 v47, v47, v48
	v_add_f32_e32 v46, v46, v47
	v_mul_f32_e32 v47, 0xbfb8aa3b, v46
	v_exp_f32_e32 v47, v47
	v_mul_f32_e32 v48, v51, v52
	v_add_f32_e32 v51, 1.0, v53
	v_rcp_f32_e32 v51, v51
	v_add_f32_e32 v47, 1.0, v47
	v_rcp_f32_e32 v47, v47
	v_mul_f32_e32 v46, v38, v46
	v_mul_f32_e32 v49, v39, v49
	v_mul_f32_e32 v49, v49, v51
	v_mul_f32_e32 v46, v46, v47
	v_cvt_pk_bf16_f32 v56, v46, v49
	v_cvt_pk_bf16_f32 v57, v48, v50
	v_cvt_pk_bf16_f32 v46, v34, v35
	s_nop 0
	v_cvt_pk_bf16_f32 v46, v36, v37
	v_cvt_pk_bf16_f32 v38, v38, v39
	s_nop 0
	v_cvt_pk_bf16_f32 v38, v40, v41
	v_or_b32_e32 v40, 16, v60
	v_mov_b64_e32 v[38:39], s[22:23]
	v_mad_i64_i32 v[40:41], s[16:17], v40, s78, v[38:39]
	v_lshl_add_u64 v[40:41], v[40:41], 0, v[154:155]
	global_store_dwordx4 v[40:41], v[54:57], off
	v_cndmask_b32_e64 v40, v24, v42, s[6:7]
	v_cndmask_b32_e64 v41, v24, v42, s[8:9]
	s_nop 1
	v_mov_b32_dpp v91, v40 row_ror:1 row_mask:0xf bank_mask:0xf
	v_mov_b32_dpp v42, v41 row_ror:2 row_mask:0xf bank_mask:0xf
	v_cndmask_b32_e64 v40, v25, v43, s[6:7]
	v_cndmask_b32_e64 v41, v25, v43, s[8:9]
	s_nop 1
	v_mov_b32_dpp v153, v40 row_ror:1 row_mask:0xf bank_mask:0xf
	v_mov_b32_dpp v43, v41 row_ror:2 row_mask:0xf bank_mask:0xf
	v_cndmask_b32_e64 v40, v27, v45, s[6:7]
	v_cndmask_b32_e64 v41, v27, v45, s[8:9]
	s_nop 1
	v_mov_b32_dpp v151, v40 row_ror:1 row_mask:0xf bank_mask:0xf
	v_mov_b32_dpp v45, v41 row_ror:2 row_mask:0xf bank_mask:0xf
	v_mov_b32_e32 v40, v27
	v_mov_b32_e32 v41, v97
	v_cndmask_b32_e64 v46, v26, v44, s[6:7]
	v_pk_mul_f32 v[40:41], v[40:41], v[150:151]
	v_fma_f32 v45, v89, v45, v105
	v_add_f32_e32 v41, v41, v45
	v_add_f32_e32 v45, v40, v41
	v_mul_f32_e32 v40, 0xbfb8aa3b, v45
	v_exp_f32_e32 v40, v40
	v_cndmask_b32_e64 v41, v26, v44, s[8:9]
	v_mov_b32_dpp v93, v46 row_ror:1 row_mask:0xf bank_mask:0xf
	s_nop 1
	v_mov_b32_dpp v44, v41 row_ror:2 row_mask:0xf bank_mask:0xf
	v_add_f32_e32 v40, 1.0, v40
	v_rcp_f32_e32 v46, v40
	v_mov_b32_e32 v40, v26
	v_mov_b32_e32 v41, v96
	v_pk_mul_f32 v[40:41], v[40:41], v[92:93]
	v_fma_f32 v44, v88, v44, v104
	v_add_f32_e32 v41, v41, v44
	v_add_f32_e32 v40, v40, v41
	v_mul_f32_e32 v41, 0xbfb8aa3b, v40
	v_exp_f32_e32 v41, v41
	v_mul_f32_e32 v44, v31, v45
	v_mul_f32_e32 v45, v30, v40
	v_mul_f32_e32 v44, v44, v46
	v_add_f32_e32 v40, 1.0, v41
	v_rcp_f32_e32 v46, v40
	v_mov_b32_e32 v40, v25
	v_mov_b32_e32 v41, v95
	v_pk_mul_f32 v[40:41], v[40:41], v[152:153]
	v_fma_f32 v43, v87, v43, v103
	v_add_f32_e32 v41, v41, v43
	v_add_f32_e32 v43, v40, v41
	v_mul_f32_e32 v40, 0xbfb8aa3b, v43
; __device__ __forceinline__ unsigned cvt_pk_bf16(float lo, float hi) { unsigned r; asm volatile("v_cvt_pk_bf16_f32 %0, %1, %2" : "=v"(r) : "v"(lo), "v"(hi)); return r; }
;     __device__ __forceinline__ void operator()(const f32x4 (&acc)[2][2][4][2], const Unit& u, int wr, int wc, int fr, int fq) const {
;     ...
;                 for (int n = 0; n < 2; ++n) {
;                     const f32x4 g = acc[ai][0][m][n], uu = acc[ai][1][m][n], gp = acc[ai][0][m > 0 ? m - 1 : 0][n];
;                     f32x4 r;
; #pragma unroll
;                     for (int e = 0; e < 4; ++e) {
;                         const float s1 = (fr == 15) ? gp[e] : g[e], s2 = (fr >= 14) ? gp[e] : g[e];
;                         const float p1 = __int_as_float(__builtin_amdgcn_ds_bpermute(src1, __float_as_int(s1))), p2 = __int_as_float(__builtin_amdgcn_ds_bpermute(src2, __float_as_int(s2)));
;                         const float c = bb[n][e] + w0[n][e] * p2 + w1[n][e] * p1 + w2[n][e] * g[e];
;                         r[e] = c * uu[e] * __builtin_amdgcn_rcpf(1.0f + __builtin_amdgcn_exp2f(c * -1.4426950408889634f));
;                     }
;                     if (n == 0) { wa.x = cvt_pk_bf16(r[0], r[1]); wa.y = cvt_pk_bf16(r[2], r[3]); wg.x = cvt_pk_bf16(g[0], g[1]); wg.y = cvt_pk_bf16(g[2], g[3]); wu.x = cvt_pk_bf16(uu[0], uu[1]); wu.y = cvt_pk_bf16(uu[2], uu[3]); }
;                     else { wa.z = cvt_pk_bf16(r[0], r[1]); wa.w = cvt_pk_bf16(r[2], r[3]); wg.z = cvt_pk_bf16(g[0], g[1]); wg.w = cvt_pk_bf16(g[2], g[3]); wu.z = cvt_pk_bf16(uu[0], uu[1]); wu.w = cvt_pk_bf16(uu[2], uu[3]); }
;                 }
;                 if (m == 0 && fr < 2) {
;                     *(u32x4*)(hg + (size_t)(blk * 4 + 2 + fr) * dff + f0) = wg; *(u32x4*)(hu + (size_t)(blk * 2 + fr) * dff + f0) = wu;
;                 } else {
;                     *(u32x4*)(act + (size_t)(rowb + m * 16 + fr) * dff + f0) = wa;
	v_exp_f32_e32 v47, v40
	v_mov_b32_e32 v40, v24
	v_mov_b32_e32 v41, v94
	v_pk_mul_f32 v[40:41], v[40:41], v[90:91]
	v_fma_f32 v42, v86, v42, v102
	v_add_f32_e32 v41, v41, v42
	v_add_f32_e32 v40, v40, v41
	v_mul_f32_e32 v41, 0xbfb8aa3b, v40
	v_exp_f32_e32 v41, v41
	v_mul_f32_e32 v42, v45, v46
	v_add_f32_e32 v45, 1.0, v47
	v_rcp_f32_e32 v45, v45
	v_add_f32_e32 v41, 1.0, v41
	v_rcp_f32_e32 v41, v41
	v_mul_f32_e32 v40, v28, v40
	v_mul_f32_e32 v43, v29, v43
	v_mul_f32_e32 v43, v43, v45
	v_mul_f32_e32 v40, v40, v41
	v_cvt_pk_bf16_f32 v40, v40, v43
	v_cvt_pk_bf16_f32 v41, v42, v44
	v_cvt_pk_bf16_f32 v42, v24, v25
	s_nop 0
	v_cvt_pk_bf16_f32 v42, v26, v27
	v_cvt_pk_bf16_f32 v28, v28, v29
	v_cndmask_b32_e64 v29, v12, v34, s[8:9]
	v_cvt_pk_bf16_f32 v28, v30, v31
	s_nop 1
	v_mov_b32_dpp v30, v29 row_ror:2 row_mask:0xf bank_mask:0xf
	v_cndmask_b32_e64 v28, v12, v34, s[6:7]
	s_nop 1
	v_mov_b32_dpp v75, v28 row_ror:1 row_mask:0xf bank_mask:0xf
	v_cndmask_b32_e64 v28, v13, v35, s[6:7]
	v_cndmask_b32_e64 v29, v13, v35, s[8:9]
	s_nop 1
	v_mov_b32_dpp v145, v28 row_ror:1 row_mask:0xf bank_mask:0xf
	v_mov_b32_dpp v31, v29 row_ror:2 row_mask:0xf bank_mask:0xf
	v_cndmask_b32_e64 v28, v15, v37, s[6:7]
	v_cndmask_b32_e64 v29, v15, v37, s[8:9]
	s_nop 1
	v_mov_b32_dpp v143, v28 row_ror:1 row_mask:0xf bank_mask:0xf
	v_mov_b32_dpp v34, v29 row_ror:2 row_mask:0xf bank_mask:0xf
	v_mov_b32_e32 v28, v15
	v_mov_b32_e32 v29, v81
	v_cndmask_b32_e64 v35, v14, v36, s[6:7]
	v_pk_mul_f32 v[28:29], v[28:29], v[142:143]
	v_fma_f32 v34, v69, v34, v73
	v_add_f32_e32 v29, v29, v34
	v_add_f32_e32 v34, v28, v29
	v_mul_f32_e32 v28, 0xbfb8aa3b, v34
	v_exp_f32_e32 v28, v28
	v_cndmask_b32_e64 v29, v14, v36, s[8:9]
	v_mov_b32_dpp v77, v35 row_ror:1 row_mask:0xf bank_mask:0xf
	s_nop 1
	v_mov_b32_dpp v35, v29 row_ror:2 row_mask:0xf bank_mask:0xf
	v_add_f32_e32 v28, 1.0, v28
	v_rcp_f32_e32 v36, v28
	v_mov_b32_e32 v28, v14
	v_mov_b32_e32 v29, v80
	v_pk_mul_f32 v[28:29], v[28:29], v[76:77]
	v_fma_f32 v35, v68, v35, v72
	v_add_f32_e32 v29, v29, v35
	v_add_f32_e32 v28, v28, v29
	v_mul_f32_e32 v29, 0xbfb8aa3b, v28
	v_exp_f32_e32 v29, v29
	v_mul_f32_e32 v34, v23, v34
	v_mul_f32_e32 v35, v22, v28
	v_mul_f32_e32 v34, v34, v36
	v_add_f32_e32 v28, 1.0, v29
	v_rcp_f32_e32 v36, v28
	v_mov_b32_e32 v28, v13
	v_mov_b32_e32 v29, v79
	v_pk_mul_f32 v[28:29], v[28:29], v[144:145]
	v_fma_f32 v31, v67, v31, v71
	v_add_f32_e32 v29, v29, v31
	v_add_f32_e32 v31, v28, v29
	v_mul_f32_e32 v28, 0xbfb8aa3b, v31
	v_exp_f32_e32 v37, v28
	v_mov_b32_e32 v28, v12
	v_mov_b32_e32 v29, v78
	v_pk_mul_f32 v[28:29], v[28:29], v[74:75]
	v_fma_f32 v30, v66, v30, v70
	v_add_f32_e32 v29, v29, v30
	v_add_f32_e32 v28, v28, v29
	v_mul_f32_e32 v29, 0xbfb8aa3b, v28
	v_exp_f32_e32 v29, v29
	v_mul_f32_e32 v30, v35, v36
	v_add_f32_e32 v35, 1.0, v37
	v_rcp_f32_e32 v35, v35
	v_add_f32_e32 v29, 1.0, v29
	v_rcp_f32_e32 v29, v29
	v_mul_f32_e32 v28, v20, v28
	v_mul_f32_e32 v31, v21, v31
	v_mul_f32_e32 v31, v31, v35
	v_mul_f32_e32 v28, v28, v29
	v_cvt_pk_bf16_f32 v42, v28, v31
	v_cvt_pk_bf16_f32 v43, v30, v34
	v_cvt_pk_bf16_f32 v28, v12, v13
	s_nop 0
	v_cvt_pk_bf16_f32 v28, v14, v15
	v_cvt_pk_bf16_f32 v20, v20, v21
	s_nop 0
	v_cvt_pk_bf16_f32 v20, v22, v23
	s_nop 0
	v_or_b32_e32 v20, 32, v60
	v_mad_i64_i32 v[20:21], s[16:17], v20, s78, v[38:39]
	v_lshl_add_u64 v[20:21], v[20:21], 0, v[154:155]
	global_store_dwordx4 v[20:21], v[40:43], off
	v_cndmask_b32_e64 v20, v16, v24, s[6:7]
	v_cndmask_b32_e64 v21, v16, v24, s[8:9]
	s_nop 1
	v_mov_b32_dpp v91, v20 row_ror:1 row_mask:0xf bank_mask:0xf
	v_mov_b32_dpp v22, v21 row_ror:2 row_mask:0xf bank_mask:0xf
	v_cndmask_b32_e64 v20, v17, v25, s[6:7]
	v_cndmask_b32_e64 v21, v17, v25, s[8:9]
	s_nop 1
	v_mov_b32_dpp v153, v20 row_ror:1 row_mask:0xf bank_mask:0xf
	v_mov_b32_dpp v23, v21 row_ror:2 row_mask:0xf bank_mask:0xf
	v_cndmask_b32_e64 v20, v19, v27, s[6:7]
	v_cndmask_b32_e64 v21, v19, v27, s[8:9]
	s_nop 1
	v_mov_b32_dpp v151, v20 row_ror:1 row_mask:0xf bank_mask:0xf
	v_mov_b32_dpp v24, v21 row_ror:2 row_mask:0xf bank_mask:0xf
	v_mov_b32_e32 v20, v19
	v_mov_b32_e32 v21, v97
	v_cndmask_b32_e64 v25, v18, v26, s[6:7]
	v_pk_mul_f32 v[20:21], v[20:21], v[150:151]
	v_fma_f32 v24, v89, v24, v105
	v_add_f32_e32 v21, v21, v24
	v_add_f32_e32 v24, v20, v21
	v_mul_f32_e32 v20, 0xbfb8aa3b, v24
	v_exp_f32_e32 v20, v20
; __device__ __forceinline__ unsigned cvt_pk_bf16(float lo, float hi) { unsigned r; asm volatile("v_cvt_pk_bf16_f32 %0, %1, %2" : "=v"(r) : "v"(lo), "v"(hi)); return r; }
;     __device__ __forceinline__ void operator()(const f32x4 (&acc)[2][2][4][2], const Unit& u, int wr, int wc, int fr, int fq) const {
;     ...
;                 for (int n = 0; n < 2; ++n) {
;                     const f32x4 g = acc[ai][0][m][n], uu = acc[ai][1][m][n], gp = acc[ai][0][m > 0 ? m - 1 : 0][n];
;                     f32x4 r;
; #pragma unroll
;                     for (int e = 0; e < 4; ++e) {
;                         const float s1 = (fr == 15) ? gp[e] : g[e], s2 = (fr >= 14) ? gp[e] : g[e];
;                         const float p1 = __int_as_float(__builtin_amdgcn_ds_bpermute(src1, __float_as_int(s1))), p2 = __int_as_float(__builtin_amdgcn_ds_bpermute(src2, __float_as_int(s2)));
;                         const float c = bb[n][e] + w0[n][e] * p2 + w1[n][e] * p1 + w2[n][e] * g[e];
;                         r[e] = c * uu[e] * __builtin_amdgcn_rcpf(1.0f + __builtin_amdgcn_exp2f(c * -1.4426950408889634f));
;                     }
;                     if (n == 0) { wa.x = cvt_pk_bf16(r[0], r[1]); wa.y = cvt_pk_bf16(r[2], r[3]); wg.x = cvt_pk_bf16(g[0], g[1]); wg.y = cvt_pk_bf16(g[2], g[3]); wu.x = cvt_pk_bf16(uu[0], uu[1]); wu.y = cvt_pk_bf16(uu[2], uu[3]); }
;                     else { wa.z = cvt_pk_bf16(r[0], r[1]); wa.w = cvt_pk_bf16(r[2], r[3]); wg.z = cvt_pk_bf16(g[0], g[1]); wg.w = cvt_pk_bf16(g[2], g[3]); wu.z = cvt_pk_bf16(uu[0], uu[1]); wu.w = cvt_pk_bf16(uu[2], uu[3]); }
;                 }
;                 if (m == 0 && fr < 2) {
;                     *(u32x4*)(hg + (size_t)(blk * 4 + 2 + fr) * dff + f0) = wg; *(u32x4*)(hu + (size_t)(blk * 2 + fr) * dff + f0) = wu;
;                 } else {
;                     *(u32x4*)(act + (size_t)(rowb + m * 16 + fr) * dff + f0) = wa;
;                 }
;                 if (m == 3 && fr >= 14) *(u32x4*)(hg + (size_t)(blk * 4 + fr - 14) * dff + f0) = wg;
	v_cndmask_b32_e64 v21, v18, v26, s[8:9]
	v_mov_b32_dpp v93, v25 row_ror:1 row_mask:0xf bank_mask:0xf
	s_nop 1
	v_mov_b32_dpp v25, v21 row_ror:2 row_mask:0xf bank_mask:0xf
	v_add_f32_e32 v20, 1.0, v20
	v_rcp_f32_e32 v26, v20
	v_mov_b32_e32 v20, v18
	v_mov_b32_e32 v21, v96
	v_pk_mul_f32 v[20:21], v[20:21], v[92:93]
	v_fma_f32 v25, v88, v25, v104
	v_add_f32_e32 v21, v21, v25
	v_add_f32_e32 v20, v20, v21
	v_mul_f32_e32 v21, 0xbfb8aa3b, v20
	v_exp_f32_e32 v21, v21
	v_mul_f32_e32 v24, v11, v24
	v_mul_f32_e32 v25, v10, v20
	v_mul_f32_e32 v24, v24, v26
	v_add_f32_e32 v20, 1.0, v21
	v_rcp_f32_e32 v26, v20
	v_mov_b32_e32 v20, v17
	v_mov_b32_e32 v21, v95
	v_pk_mul_f32 v[20:21], v[20:21], v[152:153]
	v_fma_f32 v23, v87, v23, v103
	v_add_f32_e32 v21, v21, v23
	v_add_f32_e32 v23, v20, v21
	v_mul_f32_e32 v20, 0xbfb8aa3b, v23
	v_exp_f32_e32 v27, v20
	v_mov_b32_e32 v20, v16
	v_mov_b32_e32 v21, v94
	v_pk_mul_f32 v[20:21], v[20:21], v[90:91]
	v_fmac_f32_e32 v102, v86, v22
	v_add_f32_e32 v21, v21, v102
	v_add_f32_e32 v20, v20, v21
	v_mul_f32_e32 v21, 0xbfb8aa3b, v20
	v_exp_f32_e32 v21, v21
	v_mul_f32_e32 v22, v25, v26
	v_add_f32_e32 v25, 1.0, v27
	v_rcp_f32_e32 v25, v25
	v_add_f32_e32 v21, 1.0, v21
	v_rcp_f32_e32 v21, v21
	v_mul_f32_e32 v20, v8, v20
	v_mul_f32_e32 v23, v9, v23
	v_mul_f32_e32 v23, v23, v25
	v_mul_f32_e32 v20, v20, v21
	v_cvt_pk_bf16_f32 v20, v20, v23
	v_cvt_pk_bf16_f32 v21, v22, v24
	v_cvt_pk_bf16_f32 v16, v16, v17
	v_cvt_pk_bf16_f32 v17, v18, v19
	v_cvt_pk_bf16_f32 v8, v8, v9
	v_cndmask_b32_e64 v9, v4, v12, s[8:9]
	v_cvt_pk_bf16_f32 v8, v10, v11
	s_nop 1
	v_mov_b32_dpp v10, v9 row_ror:2 row_mask:0xf bank_mask:0xf
	v_cndmask_b32_e64 v8, v4, v12, s[6:7]
	s_nop 1
	v_mov_b32_dpp v75, v8 row_ror:1 row_mask:0xf bank_mask:0xf
	v_cndmask_b32_e64 v8, v5, v13, s[6:7]
	v_cndmask_b32_e64 v9, v5, v13, s[8:9]
	s_nop 1
	v_mov_b32_dpp v145, v8 row_ror:1 row_mask:0xf bank_mask:0xf
	v_mov_b32_dpp v11, v9 row_ror:2 row_mask:0xf bank_mask:0xf
	v_cndmask_b32_e64 v8, v7, v15, s[6:7]
	v_cndmask_b32_e64 v9, v7, v15, s[8:9]
	s_nop 1
	v_mov_b32_dpp v143, v8 row_ror:1 row_mask:0xf bank_mask:0xf
	v_mov_b32_dpp v12, v9 row_ror:2 row_mask:0xf bank_mask:0xf
	v_mov_b32_e32 v8, v7
	v_mov_b32_e32 v9, v81
	v_cndmask_b32_e64 v13, v6, v14, s[6:7]
	v_pk_mul_f32 v[8:9], v[8:9], v[142:143]
	v_fma_f32 v12, v69, v12, v73
	v_add_f32_e32 v9, v9, v12
	v_add_f32_e32 v12, v8, v9
	v_mul_f32_e32 v8, 0xbfb8aa3b, v12
	v_exp_f32_e32 v8, v8
	v_cndmask_b32_e64 v9, v6, v14, s[8:9]
	v_mov_b32_dpp v77, v13 row_ror:1 row_mask:0xf bank_mask:0xf
	s_nop 1
	v_mov_b32_dpp v13, v9 row_ror:2 row_mask:0xf bank_mask:0xf
	v_add_f32_e32 v8, 1.0, v8
	v_rcp_f32_e32 v14, v8
	v_mov_b32_e32 v8, v6
	v_mov_b32_e32 v9, v80
	v_pk_mul_f32 v[8:9], v[8:9], v[76:77]
	v_fma_f32 v13, v68, v13, v72
	v_add_f32_e32 v9, v9, v13
	v_add_f32_e32 v8, v8, v9
	v_mul_f32_e32 v9, 0xbfb8aa3b, v8
	v_exp_f32_e32 v9, v9
	v_mul_f32_e32 v12, v3, v12
	v_mul_f32_e32 v13, v2, v8
	v_mul_f32_e32 v12, v12, v14
	v_add_f32_e32 v8, 1.0, v9
	v_rcp_f32_e32 v14, v8
	v_mov_b32_e32 v8, v5
	v_mov_b32_e32 v9, v79
	v_pk_mul_f32 v[8:9], v[8:9], v[144:145]
	v_fma_f32 v11, v67, v11, v71
	v_add_f32_e32 v9, v9, v11
	v_add_f32_e32 v11, v8, v9
	v_mul_f32_e32 v8, 0xbfb8aa3b, v11
	v_exp_f32_e32 v15, v8
	v_mov_b32_e32 v8, v4
	v_mov_b32_e32 v9, v78
	v_pk_mul_f32 v[8:9], v[8:9], v[74:75]
	v_fmac_f32_e32 v70, v66, v10
	v_add_f32_e32 v9, v9, v70
	v_add_f32_e32 v8, v8, v9
	v_mul_f32_e32 v9, 0xbfb8aa3b, v8
	v_exp_f32_e32 v9, v9
	v_mul_f32_e32 v10, v13, v14
	v_add_f32_e32 v13, 1.0, v15
	v_rcp_f32_e32 v13, v13
	v_add_f32_e32 v9, 1.0, v9
	v_rcp_f32_e32 v9, v9
	v_mul_f32_e32 v11, v1, v11
	v_mul_f32_e32 v8, v0, v8
	v_mul_f32_e32 v11, v11, v13
	v_mul_f32_e32 v8, v8, v9
	v_cvt_pk_bf16_f32 v22, v8, v11
	v_cvt_pk_bf16_f32 v23, v10, v12
	v_cvt_pk_bf16_f32 v18, v4, v5
	v_cvt_pk_bf16_f32 v19, v6, v7
	v_cvt_pk_bf16_f32 v0, v0, v1
	s_nop 0
	v_cvt_pk_bf16_f32 v0, v2, v3
	s_nop 0
	v_or_b32_e32 v0, 48, v60
	v_mad_i64_i32 v[0:1], s[16:17], v0, s78, v[38:39]
	v_lshl_add_u64 v[0:1], v[0:1], 0, v[154:155]
	global_store_dwordx4 v[0:1], v[20:23], off
	s_and_saveexec_b64 s[56:57], s[8:9]
	s_cbranch_execz .LBB0_494
	v_add_u32_e32 v2, s45, v214
	v_mov_b64_e32 v[0:1], s[28:29]
	v_mad_i64_i32 v[0:1], s[16:17], v2, s78, v[0:1]
	v_lshl_add_u64 v[0:1], v[196:197], 1, v[0:1]
	global_store_dwordx4 v[0:1], v[16:19], off
